# write-through (sc1) epilogue stores in phases 4-6 with every wave draining before the block barrier; buffer_wbl2 dropped from the three grid barriers after phases 4, 5, 6
# speedup vs baseline: 1.0990x; 1.0321x over previous
; __device__ __forceinline__ float sigmoidf_(float x) { return 1.f / (1.f + __expf(-x)); }
; __device__ __forceinline__ uint4 pack8(float4 a, float4 b) { uint4 o; o.x = cvtpk(a.x, a.y); o.y = cvtpk(a.z, a.w); o.z = cvtpk(b.x, b.y); o.w = cvtpk(b.z, b.w); return o; }
; __device__ __forceinline__ void phase4(const Params& p, unsigned char* smem) {
;     ...
;       epilogue_rows(acc, m0, n0, smem, [&](int m, int n, float4 a, float4 b) {
;         int col = n - 8208; u16* dst = col < 1024 ? SGA + col : SGD + (col - 1024);
;         a.x = sigmoidf_(a.x); a.y = sigmoidf_(a.y); a.z = sigmoidf_(a.z); a.w = sigmoidf_(a.w);
;         b.x = sigmoidf_(b.x); b.y = sigmoidf_(b.y); b.z = sigmoidf_(b.z); b.w = sigmoidf_(b.w);
;         *(uint4*)(dst + (size_t)m * 1024) = pack8(a, b);
;       });
.LBB0_376:
	s_nop 0
	v_add_u32_e32 v68, s68, v65
	v_ashrrev_i32_e32 v69, 4, v68
	v_add_u32_e32 v68, 0x100, v68
	v_mad_u64_u32 v[72:73], s[4:5], v69, s56, v[64:65]
	v_add_u32_e32 v76, s66, v69
	v_ashrrev_i32_e32 v78, 4, v68
	ds_read_b128 v[68:71], v72
	ds_read_b128 v[72:75], v72 offset:16
	v_ashrrev_i32_e32 v77, 31, v76
	v_mad_u64_u32 v[80:81], s[4:5], v78, s56, v[64:65]
	v_add_u32_e32 v84, s66, v78
	v_lshlrev_b64 v[86:87], 11, v[76:77]
	ds_read_b128 v[76:79], v80
	ds_read_b128 v[80:83], v80 offset:16
	s_waitcnt lgkmcnt(3)
	v_mul_f32_e32 v68, 0xbfb8aa3b, v68
	v_mul_f32_e32 v69, 0xbfb8aa3b, v69
	v_exp_f32_e32 v68, v68
	v_exp_f32_e32 v69, v69
	v_mul_f32_e32 v70, 0xbfb8aa3b, v70
	v_mul_f32_e32 v71, 0xbfb8aa3b, v71
	s_waitcnt lgkmcnt(1)
	v_mul_f32_e32 v76, 0xbfb8aa3b, v76
	v_mul_f32_e32 v77, 0xbfb8aa3b, v77
	v_exp_f32_e32 v70, v70
	v_exp_f32_e32 v71, v71
	v_exp_f32_e32 v76, v76
	v_exp_f32_e32 v77, v77
	v_mul_f32_e32 v72, 0xbfb8aa3b, v72
	v_mul_f32_e32 v73, 0xbfb8aa3b, v73
	v_mul_f32_e32 v78, 0xbfb8aa3b, v78
	v_mul_f32_e32 v79, 0xbfb8aa3b, v79
	v_exp_f32_e32 v72, v72
	v_exp_f32_e32 v73, v73
	v_exp_f32_e32 v78, v78
	v_exp_f32_e32 v79, v79
	v_pk_add_f32 v[68:69], v[68:69], 1.0 op_sel_hi:[1,0]
	v_mul_f32_e32 v74, 0xbfb8aa3b, v74
	v_mul_f32_e32 v75, 0xbfb8aa3b, v75
	s_waitcnt lgkmcnt(0)
	v_mul_f32_e32 v80, 0xbfb8aa3b, v80
	v_mul_f32_e32 v81, 0xbfb8aa3b, v81
	v_exp_f32_e32 v74, v74
	v_exp_f32_e32 v75, v75
	v_exp_f32_e32 v80, v80
	v_exp_f32_e32 v81, v81
	v_pk_add_f32 v[70:71], v[70:71], 1.0 op_sel_hi:[1,0]
	v_pk_add_f32 v[76:77], v[76:77], 1.0 op_sel_hi:[1,0]
	v_mul_f32_e32 v82, 0xbfb8aa3b, v82
	v_mul_f32_e32 v83, 0xbfb8aa3b, v83
	v_exp_f32_e32 v82, v82
	v_exp_f32_e32 v83, v83
	v_pk_add_f32 v[72:73], v[72:73], 1.0 op_sel_hi:[1,0]
	v_pk_add_f32 v[78:79], v[78:79], 1.0 op_sel_hi:[1,0]
	v_pk_add_f32 v[74:75], v[74:75], 1.0 op_sel_hi:[1,0]
	v_pk_add_f32 v[80:81], v[80:81], 1.0 op_sel_hi:[1,0]
	v_pk_add_f32 v[82:83], v[82:83], 1.0 op_sel_hi:[1,0]
	v_rcp_f32_e32 v69, v69
	s_nop 0
	v_rcp_f32_e32 v68, v68
	s_nop 0
	v_rcp_f32_e32 v71, v71
	s_nop 0
	v_cvt_pk_bf16_f32 v68, v68, v69
	v_rcp_f32_e32 v69, v70
	s_nop 0
	v_rcp_f32_e32 v70, v73
	s_nop 0
	v_cvt_pk_bf16_f32 v69, v69, v71
	v_rcp_f32_e32 v71, v72
	s_nop 0
	v_rcp_f32_e32 v72, v75
	s_nop 0
	v_cvt_pk_bf16_f32 v70, v71, v70
	v_rcp_f32_e32 v71, v74
	s_nop 0
	v_lshl_add_u64 v[86:87], v[66:67], 0, v[86:87]
	v_cvt_pk_bf16_f32 v71, v71, v72
	v_rcp_f32_e32 v72, v77
	s_nop 0
	global_store_dwordx4 v[86:87], v[68:71], off sc1
	s_nop 1
	v_rcp_f32_e32 v68, v76
	s_nop 0
	v_rcp_f32_e32 v69, v79
	s_nop 0
	v_cvt_pk_bf16_f32 v68, v68, v72
	v_rcp_f32_e32 v70, v78
	s_nop 0
	v_cvt_pk_bf16_f32 v69, v70, v69
	v_rcp_f32_e32 v70, v80
	s_nop 0
	v_ashrrev_i32_e32 v85, 31, v84
	v_rcp_f32_e32 v71, v81
	s_nop 0
	s_addk_i32 s68, 0x200
	v_lshlrev_b64 v[84:85], 11, v[84:85]
	v_rcp_f32_e32 v72, v83
	s_nop 0
	v_cvt_pk_bf16_f32 v70, v70, v71
	v_rcp_f32_e32 v71, v82
	s_nop 0
	s_cmpk_lg_i32 s68, 0x800
	v_lshl_add_u64 v[84:85], v[66:67], 0, v[84:85]
	v_cvt_pk_bf16_f32 v71, v71, v72
	global_store_dwordx4 v[84:85], v[68:71], off sc1
	s_cbranch_scc1 .LBB0_376
	s_barrier
	s_mov_b64 s[4:5], 0

; __device__ __forceinline__ float bflo(unsigned v) { return __uint_as_float(v << 16); }
; __device__ __forceinline__ float bfhi(unsigned v) { return __uint_as_float(v & 0xffff0000u); }
; __device__ __forceinline__ void phase4(const Params& p, unsigned char* smem) {
;     ...
;       epilogue_rows(acc, m0, n0, smem, [&](int m, int n, float4 a, float4 b) {
;         int col = n - 7168; int h = col >> 7, d = col & 127;
;         int bb = m >> 13, t = m & 8191; int bh = bb * 8 + h; int pp = t + 64;
;         uint4* ptr = (uint4*)(DX + (((size_t)(bh * NCH + (pp >> 6))) * 3) * 8192 + (pp & 63) * 128 + d);
;         uint4 o = *ptr;
;         float o0 = bflo(o.x), o1 = bfhi(o.x), o2 = bflo(o.y), o3 = bfhi(o.y), o4 = bflo(o.z), o5 = bfhi(o.z), o6 = bflo(o.w), o7 = bfhi(o.w);
;         float sq = o0 * o0 + o1 * o1 + o2 * o2 + o3 * o3 + o4 * o4 + o5 * o5 + o6 * o6 + o7 * o7;
;         sq += __shfl_xor(sq, 1); sq += __shfl_xor(sq, 2); sq += __shfl_xor(sq, 4); sq += __shfl_xor(sq, 8);
;         float rs = rsqrtf(sq * (1.f / 128.f) + 1e-6f);
.LBB0_380:
	v_add_u32_e32 v72, s68, v81
	v_ashrrev_i32_e32 v74, 4, v72
	v_add_u32_e32 v75, 0x100, v72
	v_mad_u64_u32 v[72:73], s[4:5], v74, s56, v[80:81]
	v_add_u32_e32 v73, s66, v74
	v_and_b32_e32 v76, 0x1fc0, v73
	v_ashrrev_i32_e32 v77, 10, v73
	global_load_dwordx4 v[64:67], v[82:83], off offset:16
	global_load_dwordx4 v[68:71], v[82:83], off
	ds_read_b128 v[100:103], v72
	ds_read_b128 v[104:107], v72 offset:16
	v_and_b32_e32 v94, -8, v77
	v_add_u32_e32 v95, 64, v76
	v_add_u32_e32 v109, v94, v88
	v_lshrrev_b32_e32 v94, 6, v95
	v_mov_b64_e32 v[86:87], s[42:43]
	v_lshlrev_b32_e32 v74, 8, v74
	v_mad_u64_u32 v[94:95], s[4:5], v109, s58, v[94:95]
	v_ashrrev_i32_e32 v75, 4, v75
	v_and_b32_e32 v96, 0x3f00, v74
	v_mad_i64_i32 v[94:95], s[4:5], v94, s59, v[86:87]
	v_mov_b32_e32 v85, v97
	v_mad_u64_u32 v[72:73], s[4:5], v75, s56, v[80:81]
	v_lshl_add_u64 v[94:95], v[94:95], 0, v[96:97]
	v_add_u32_e32 v73, s66, v75
	s_waitcnt lgkmcnt(1)
	v_mul_f32_e32 v116, 0xbfb8aa3b, v103
	v_mul_f32_e32 v117, 0xbfb8aa3b, v100
	v_mul_f32_e32 v118, 0xbfb8aa3b, v101
	s_waitcnt lgkmcnt(0)
	v_mul_f32_e32 v119, 0xbfb8aa3b, v106
	v_lshl_add_u64 v[94:95], v[94:95], 0, v[84:85]
	v_lshlrev_b32_e32 v93, 8, v75
	v_and_b32_e32 v98, 0x1fc0, v73
	v_ashrrev_i32_e32 v108, 10, v73
	ds_read_b128 v[76:79], v72
	ds_read_b128 v[72:75], v72 offset:16
	v_exp_f32_e32 v121, v116
	v_exp_f32_e32 v122, v117
	v_exp_f32_e32 v123, v118
	v_exp_f32_e32 v124, v119
	global_load_dwordx4 v[116:119], v[94:95], off
	v_and_b32_e32 v108, -8, v108
	v_add_u32_e32 v98, 64, v98
	v_add_u32_e32 v108, v108, v88
	v_lshrrev_b32_e32 v98, 6, v98
	v_mad_u64_u32 v[108:109], s[4:5], v108, s58, v[98:99]
	v_mul_f32_e32 v98, 0xbfb8aa3b, v104
	v_mul_f32_e32 v109, 0xbfb8aa3b, v105
	v_mad_i64_i32 v[86:87], s[4:5], v108, s59, v[86:87]
	v_and_b32_e32 v96, 0x3f00, v93
	v_exp_f32_e32 v108, v98
	v_exp_f32_e32 v109, v109
	v_mul_f32_e32 v115, 0xbfb8aa3b, v102
	v_lshl_add_u64 v[86:87], v[86:87], 0, v[96:97]
	s_waitcnt lgkmcnt(0)
	v_mul_f32_e32 v93, 0xbfb8aa3b, v72
	v_mul_f32_e32 v96, 0xbfb8aa3b, v73
	v_exp_f32_e32 v120, v115
	v_exp_f32_e32 v126, v93
	v_exp_f32_e32 v127, v96
	v_mul_f32_e32 v98, 0xbfb8aa3b, v78
	v_mul_f32_e32 v115, 0xbfb8aa3b, v79
	v_exp_f32_e32 v128, v98
	v_exp_f32_e32 v129, v115
	v_pk_add_f32 v[108:109], v[108:109], 1.0 op_sel_hi:[1,0]
	v_mul_f32_e32 v125, 0xbfb8aa3b, v107
	v_mul_f32_e32 v130, 0xbfb8aa3b, v76
	v_mul_f32_e32 v131, 0xbfb8aa3b, v77
	v_lshl_add_u64 v[86:87], v[86:87], 0, v[84:85]
	v_exp_f32_e32 v125, v125
	v_exp_f32_e32 v130, v130
	v_exp_f32_e32 v131, v131
	v_pk_add_f32 v[120:121], v[120:121], 1.0 op_sel_hi:[1,0]
	v_pk_add_f32 v[126:127], v[126:127], 1.0 op_sel_hi:[1,0]
	v_mul_f32_e32 v132, 0xbfb8aa3b, v74
	v_mul_f32_e32 v133, 0xbfb8aa3b, v75
	v_exp_f32_e32 v132, v132
	v_exp_f32_e32 v133, v133
	v_pk_add_f32 v[122:123], v[122:123], 1.0 op_sel_hi:[1,0]
	v_pk_add_f32 v[128:129], v[128:129], 1.0 op_sel_hi:[1,0]
	v_pk_add_f32 v[124:125], v[124:125], 1.0 op_sel_hi:[1,0]
	v_pk_add_f32 v[130:131], v[130:131], 1.0 op_sel_hi:[1,0]
	v_pk_add_f32 v[132:133], v[132:133], 1.0 op_sel_hi:[1,0]
	v_rcp_f32_e32 v85, v109
	s_nop 0
	v_mul_f32_e32 v105, v105, v85
	v_rcp_f32_e32 v85, v108
	s_nop 0
	v_mul_f32_e32 v104, v104, v85
	v_rcp_f32_e32 v85, v121
	s_nop 0
	v_mul_f32_e32 v103, v103, v85
	v_rcp_f32_e32 v85, v120
	s_nop 0
	v_mul_f32_e32 v102, v102, v85
	v_rcp_f32_e32 v85, v123
	s_nop 0
	v_mul_f32_e32 v101, v101, v85
	v_rcp_f32_e32 v85, v122
	s_nop 0
	v_mul_f32_e32 v100, v100, v85
	s_waitcnt vmcnt(0)
	v_lshlrev_b32_e32 v108, 16, v116
	v_and_b32_e32 v109, 0xffff0000, v116
	v_rcp_f32_e32 v85, v125
	s_nop 0
	v_mul_f32_e32 v107, v107, v85
	v_lshlrev_b32_e32 v116, 16, v117
	v_and_b32_e32 v117, 0xffff0000, v117
	v_pk_mul_f32 v[136:137], v[108:109], v[108:109]
	v_rcp_f32_e32 v85, v124
	s_nop 0
	v_mul_f32_e32 v106, v106, v85
	v_pk_mul_f32 v[134:135], v[116:117], v[116:117]
	v_add_f32_e32 v85, v136, v137
	v_lshlrev_b32_e32 v120, 16, v118
	v_and_b32_e32 v121, 0xffff0000, v118
	v_add_f32_e32 v85, v85, v134
	v_pk_mul_f32 v[124:125], v[120:121], v[120:121]
	v_add_f32_e32 v85, v135, v85
	v_lshlrev_b32_e32 v118, 16, v119
	v_and_b32_e32 v119, 0xffff0000, v119
	v_add_f32_e32 v85, v124, v85
	v_pk_mul_f32 v[122:123], v[118:119], v[118:119]
	v_add_f32_e32 v85, v125, v85
	v_add_f32_e32 v85, v122, v85
	v_add_f32_e32 v85, v123, v85
	ds_bpermute_b32 v93, v89, v85
	s_waitcnt lgkmcnt(0)
; __device__ __forceinline__ float bflo(unsigned v) { return __uint_as_float(v << 16); }
; __device__ __forceinline__ float bfhi(unsigned v) { return __uint_as_float(v & 0xffff0000u); }
; __device__ __forceinline__ float siluf_(float x) { return x / (1.f + __expf(-x)); }
; __device__ __forceinline__ uint4 pack8(float4 a, float4 b) { uint4 o; o.x = cvtpk(a.x, a.y); o.y = cvtpk(a.z, a.w); o.z = cvtpk(b.x, b.y); o.w = cvtpk(b.z, b.w); return o; }
; __device__ __forceinline__ void phase4(const Params& p, unsigned char* smem) {
;     ...
;         int col = n - 7168; int h = col >> 7, d = col & 127;
;         int bb = m >> 13, t = m & 8191; int bh = bb * 8 + h; int pp = t + 64;
;         uint4* ptr = (uint4*)(DX + (((size_t)(bh * NCH + (pp >> 6))) * 3) * 8192 + (pp & 63) * 128 + d);
;         uint4 o = *ptr;
;         float o0 = bflo(o.x), o1 = bfhi(o.x), o2 = bflo(o.y), o3 = bfhi(o.y), o4 = bflo(o.z), o5 = bfhi(o.z), o6 = bflo(o.w), o7 = bfhi(o.w);
;         float sq = o0 * o0 + o1 * o1 + o2 * o2 + o3 * o3 + o4 * o4 + o5 * o5 + o6 * o6 + o7 * o7;
;         sq += __shfl_xor(sq, 1); sq += __shfl_xor(sq, 2); sq += __shfl_xor(sq, 4); sq += __shfl_xor(sq, 8);
;         float rs = rsqrtf(sq * (1.f / 128.f) + 1e-6f);
;         float4 w0 = *(const float4*)(p.dn_norm_w + d), w1 = *(const float4*)(p.dn_norm_w + d + 4);
;         a.x = o0 * rs * w0.x * siluf_(a.x); a.y = o1 * rs * w0.y * siluf_(a.y); a.z = o2 * rs * w0.z * siluf_(a.z); a.w = o3 * rs * w0.w * siluf_(a.w);
;         b.x = o4 * rs * w1.x * siluf_(b.x); b.y = o5 * rs * w1.y * siluf_(b.y); b.z = o6 * rs * w1.z * siluf_(b.z); b.w = o7 * rs * w1.w * siluf_(b.w);
;         *ptr = pack8(a, b);
	v_add_f32_e32 v85, v85, v93
	ds_bpermute_b32 v93, v90, v85
	s_waitcnt lgkmcnt(0)
	v_add_f32_e32 v85, v85, v93
	ds_bpermute_b32 v93, v91, v85
	s_waitcnt lgkmcnt(0)
	v_add_f32_e32 v85, v85, v93
	ds_bpermute_b32 v93, v92, v85
	s_waitcnt lgkmcnt(0)
	v_add_f32_e32 v85, v85, v93
	v_fmamk_f32 v85, v85, 0x3c000000, v110
	v_mul_f32_e32 v93, 0x4b800000, v85
	v_cmp_gt_f32_e32 vcc, s60, v85
	s_nop 1
	v_cndmask_b32_e32 v85, v85, v93, vcc
	v_rsq_f32_e32 v85, v85
	s_nop 0
	v_mul_f32_e32 v93, 0x45800000, v85
	v_cndmask_b32_e32 v96, v85, v93, vcc
	v_pk_mul_f32 v[108:109], v[96:97], v[108:109] op_sel_hi:[0,1]
	v_pk_mul_f32 v[116:117], v[96:97], v[116:117] op_sel_hi:[0,1]
	v_pk_mul_f32 v[120:121], v[96:97], v[120:121] op_sel_hi:[0,1]
	v_pk_mul_f32 v[118:119], v[96:97], v[118:119] op_sel_hi:[0,1]
	v_pk_mul_f32 v[68:69], v[68:69], v[108:109]
	v_pk_mul_f32 v[70:71], v[70:71], v[116:117]
	v_pk_mul_f32 v[64:65], v[64:65], v[120:121]
	v_pk_mul_f32 v[66:67], v[66:67], v[118:119]
	v_pk_mul_f32 v[68:69], v[100:101], v[68:69]
	v_pk_mul_f32 v[70:71], v[102:103], v[70:71]
	v_pk_mul_f32 v[100:101], v[104:105], v[64:65]
	v_pk_mul_f32 v[102:103], v[106:107], v[66:67]
	v_cvt_pk_bf16_f32 v64, v68, v69
	v_cvt_pk_bf16_f32 v65, v70, v71
	v_cvt_pk_bf16_f32 v66, v100, v101
	v_cvt_pk_bf16_f32 v67, v102, v103
	global_store_dwordx4 v[94:95], v[64:67], off sc1
	s_nop 1
	global_load_dwordx4 v[64:67], v[86:87], off
	v_rcp_f32_e32 v68, v127
	s_nop 0
	v_mul_f32_e32 v73, v73, v68
	v_rcp_f32_e32 v68, v126
	s_nop 0
	v_mul_f32_e32 v72, v72, v68
	v_rcp_f32_e32 v68, v129
	s_nop 0
	v_mul_f32_e32 v79, v79, v68
	global_load_dwordx4 v[68:71], v[82:83], off
	global_load_dwordx4 v[100:103], v[82:83], off offset:16
	v_rcp_f32_e32 v85, v131
	s_nop 0
	v_mul_f32_e32 v77, v77, v85
	v_rcp_f32_e32 v85, v130
	s_nop 0
	v_mul_f32_e32 v76, v76, v85
	v_rcp_f32_e32 v85, v133
	s_nop 0
	v_mul_f32_e32 v75, v75, v85
	v_rcp_f32_e32 v85, v132
	s_nop 0
	v_mul_f32_e32 v74, v74, v85
	v_rcp_f32_e32 v96, v128
	s_nop 0
	v_mul_f32_e32 v78, v78, v96
	s_addk_i32 s68, 0x200
	s_cmpk_lg_i32 s68, 0x800
	s_waitcnt vmcnt(2)
	v_lshlrev_b32_e32 v94, 16, v64
	v_and_b32_e32 v95, 0xffff0000, v64
	v_lshlrev_b32_e32 v64, 16, v65
	v_and_b32_e32 v65, 0xffff0000, v65
	v_pk_mul_f32 v[118:119], v[94:95], v[94:95]
	v_pk_mul_f32 v[116:117], v[64:65], v[64:65]
	v_add_f32_e32 v85, v118, v119
	v_lshlrev_b32_e32 v104, 16, v66
	v_and_b32_e32 v105, 0xffff0000, v66
	v_add_f32_e32 v85, v85, v116
	v_pk_mul_f32 v[108:109], v[104:105], v[104:105]
	v_add_f32_e32 v85, v117, v85
	v_lshlrev_b32_e32 v66, 16, v67
	v_and_b32_e32 v67, 0xffff0000, v67
	v_add_f32_e32 v85, v108, v85
	v_pk_mul_f32 v[106:107], v[66:67], v[66:67]
	v_add_f32_e32 v85, v109, v85
	v_add_f32_e32 v85, v106, v85
	v_add_f32_e32 v85, v107, v85
	ds_bpermute_b32 v93, v89, v85
	s_waitcnt lgkmcnt(0)
	v_add_f32_e32 v85, v85, v93
	ds_bpermute_b32 v93, v90, v85
	s_waitcnt lgkmcnt(0)
	v_add_f32_e32 v85, v85, v93
	ds_bpermute_b32 v93, v91, v85
	s_waitcnt lgkmcnt(0)
	v_add_f32_e32 v85, v85, v93
	ds_bpermute_b32 v93, v92, v85
	s_waitcnt lgkmcnt(0)
	v_add_f32_e32 v85, v85, v93
	v_fmamk_f32 v85, v85, 0x3c000000, v110
	v_mul_f32_e32 v93, 0x4b800000, v85
	v_cmp_gt_f32_e32 vcc, s60, v85
	s_nop 1
	s_nop 0
	v_cndmask_b32_e32 v85, v85, v93, vcc
	v_rsq_f32_e32 v85, v85
	s_nop 0
	v_mul_f32_e32 v93, 0x45800000, v85
	v_cndmask_b32_e32 v96, v85, v93, vcc
	v_pk_mul_f32 v[94:95], v[96:97], v[94:95] op_sel_hi:[0,1]
	v_pk_mul_f32 v[64:65], v[96:97], v[64:65] op_sel_hi:[0,1]
	v_pk_mul_f32 v[104:105], v[96:97], v[104:105] op_sel_hi:[0,1]
	v_pk_mul_f32 v[66:67], v[96:97], v[66:67] op_sel_hi:[0,1]
	s_waitcnt vmcnt(1)
	v_pk_mul_f32 v[68:69], v[68:69], v[94:95]
	v_pk_mul_f32 v[64:65], v[70:71], v[64:65]
	s_waitcnt vmcnt(0)
	v_pk_mul_f32 v[70:71], v[100:101], v[104:105]
	v_pk_mul_f32 v[66:67], v[102:103], v[66:67]
	v_pk_mul_f32 v[68:69], v[76:77], v[68:69]
	v_pk_mul_f32 v[76:77], v[78:79], v[64:65]
	v_pk_mul_f32 v[70:71], v[72:73], v[70:71]
	v_pk_mul_f32 v[72:73], v[74:75], v[66:67]
	v_cvt_pk_bf16_f32 v64, v68, v69
	v_cvt_pk_bf16_f32 v65, v76, v77
	v_cvt_pk_bf16_f32 v66, v70, v71
	v_cvt_pk_bf16_f32 v67, v72, v73
	global_store_dwordx4 v[86:87], v[64:67], off sc1
	s_cbranch_scc1 .LBB0_380
	s_barrier

; __device__ __forceinline__ float bflo(unsigned v) { return __uint_as_float(v << 16); }
; __device__ __forceinline__ float bfhi(unsigned v) { return __uint_as_float(v & 0xffff0000u); }
; __device__ __forceinline__ float siluf_(float x) { return x / (1.f + __expf(-x)); }
; __device__ __forceinline__ uint4 pack8(float4 a, float4 b) { uint4 o; o.x = cvtpk(a.x, a.y); o.y = cvtpk(a.z, a.w); o.z = cvtpk(b.x, b.y); o.w = cvtpk(b.z, b.w); return o; }
; __device__ __forceinline__ void grid_barrier(unsigned* ctr, const unsigned k) {
;   __syncthreads();
;   if (threadIdx.x == 0) {
;     __hip_atomic_fetch_add(ctr, 1u, __ATOMIC_RELEASE, __HIP_MEMORY_SCOPE_AGENT);
;     const unsigned target = k * gridDim.x;
;     while (__hip_atomic_load(ctr, __ATOMIC_RELAXED, __HIP_MEMORY_SCOPE_AGENT) < target) __builtin_amdgcn_s_sleep(1);
;     __builtin_amdgcn_fence(__ATOMIC_ACQUIRE, "agent");
;   }
;   __syncthreads();
; __device__ __forceinline__ void phase4(const Params& p, unsigned char* smem) {
;     ...
;       epilogue_rows(acc, m0, n0, smem, [&](int m, int n, float4 a, float4 b) {
;         uint4* ptr = (uint4*)(AQ + (size_t)tokrow_of(m) * 1024 + (n - 3072));
;         uint4 o = *ptr;
;         a.x = bflo(o.x) * siluf_(a.x); a.y = bfhi(o.x) * siluf_(a.y); a.z = bflo(o.y) * siluf_(a.z); a.w = bfhi(o.y) * siluf_(a.w);
;         b.x = bflo(o.z) * siluf_(b.x); b.y = bfhi(o.z) * siluf_(b.y); b.z = bflo(o.w) * siluf_(b.z); b.w = bfhi(o.w) * siluf_(b.w);
;         *ptr = pack8(a, b);
;       });
.LBB0_385:
	s_nop 0
	v_add_u32_e32 v0, s67, v9
	v_ashrrev_i32_e32 v2, 4, v0
	v_add_u32_e32 v3, 0x100, v0
	v_mad_u64_u32 v[0:1], s[4:5], v2, s56, v[8:9]
	v_add_u32_e32 v1, s66, v2
	v_ashrrev_i32_e32 v2, 4, v3
	v_ashrrev_i32_e32 v3, 13, v1
	v_and_b32_e32 v20, 0x1fff, v1
	ds_read_b128 v[12:15], v0
	ds_read_b128 v[16:19], v0 offset:16
	v_mad_u64_u32 v[0:1], s[4:5], v2, s56, v[8:9]
	v_add_u32_e32 v1, s66, v2
	v_mul_i32_i24_e32 v21, 0x2010, v3
	v_ashrrev_i32_e32 v22, 13, v1
	v_add3_u32 v20, v20, v21, 16
	v_and_b32_e32 v23, 0x1fff, v1
	v_mul_i32_i24_e32 v22, 0x2010, v22
	v_ashrrev_i32_e32 v21, 31, v20
	ds_read_b128 v[4:7], v0
	ds_read_b128 v[0:3], v0 offset:16
	v_add3_u32 v22, v23, v22, 16
	v_lshlrev_b64 v[20:21], 11, v[20:21]
	v_ashrrev_i32_e32 v23, 31, v22
	v_lshl_add_u64 v[20:21], v[10:11], 0, v[20:21]
	s_waitcnt lgkmcnt(3)
	v_mul_f32_e32 v25, 0xbfb8aa3b, v12
	v_lshlrev_b64 v[22:23], 11, v[22:23]
	v_add_co_u32_e32 v24, vcc, s61, v20
	v_exp_f32_e32 v26, v25
	v_lshl_add_u64 v[22:23], v[10:11], 0, v[22:23]
	v_addc_co_u32_e32 v25, vcc, -1, v21, vcc
	s_waitcnt lgkmcnt(1)
	v_mul_f32_e32 v20, 0xbfb8aa3b, v4
	v_add_co_u32_e32 v34, vcc, s61, v22
	v_exp_f32_e32 v36, v20
	s_nop 0
	v_addc_co_u32_e32 v35, vcc, -1, v23, vcc
	global_load_dwordx4 v[20:23], v[24:25], off offset:-2048
	v_mul_f32_e32 v27, 0xbfb8aa3b, v13
	v_mul_f32_e32 v32, 0xbfb8aa3b, v18
	v_mul_f32_e32 v33, 0xbfb8aa3b, v19
	v_exp_f32_e32 v27, v27
	v_mul_f32_e32 v28, 0xbfb8aa3b, v14
	v_mul_f32_e32 v29, 0xbfb8aa3b, v15
	v_exp_f32_e32 v32, v32
	v_exp_f32_e32 v33, v33
	v_exp_f32_e32 v28, v28
	v_exp_f32_e32 v29, v29
	v_mul_f32_e32 v30, 0xbfb8aa3b, v16
	v_mul_f32_e32 v31, 0xbfb8aa3b, v17
	v_exp_f32_e32 v30, v30
	v_exp_f32_e32 v31, v31
	v_pk_add_f32 v[26:27], v[26:27], 1.0 op_sel_hi:[1,0]
	v_pk_add_f32 v[32:33], v[32:33], 1.0 op_sel_hi:[1,0]
	v_pk_add_f32 v[28:29], v[28:29], 1.0 op_sel_hi:[1,0]
	v_pk_add_f32 v[30:31], v[30:31], 1.0 op_sel_hi:[1,0]
	s_waitcnt vmcnt(1)
	v_rcp_f32_e32 v44, v27
	s_nop 0
	v_mul_f32_e32 v13, v13, v44
	v_rcp_f32_e32 v27, v26
	s_nop 0
	v_mul_f32_e32 v12, v12, v27
	v_rcp_f32_e32 v26, v29
	s_nop 0
	v_mul_f32_e32 v15, v15, v26
	v_rcp_f32_e32 v26, v28
	s_nop 0
	v_mul_f32_e32 v14, v14, v26
	v_rcp_f32_e32 v26, v31
	s_nop 0
	v_mul_f32_e32 v17, v17, v26
	v_rcp_f32_e32 v26, v30
	s_nop 0
	v_mul_f32_e32 v16, v16, v26
	v_rcp_f32_e32 v26, v33
	s_nop 0
	v_mul_f32_e32 v19, v19, v26
	v_rcp_f32_e32 v26, v32
	s_nop 0
	v_mul_f32_e32 v18, v18, v26
	s_waitcnt vmcnt(0)
	v_lshlrev_b32_e32 v26, 16, v20
	v_and_b32_e32 v27, 0xffff0000, v20
	v_lshlrev_b32_e32 v20, 16, v21
	v_and_b32_e32 v21, 0xffff0000, v21
	v_lshlrev_b32_e32 v28, 16, v22
	v_and_b32_e32 v29, 0xffff0000, v22
	v_lshlrev_b32_e32 v22, 16, v23
	v_and_b32_e32 v23, 0xffff0000, v23
	v_pk_mul_f32 v[12:13], v[12:13], v[26:27]
	v_pk_mul_f32 v[14:15], v[14:15], v[20:21]
	v_pk_mul_f32 v[16:17], v[16:17], v[28:29]
	v_pk_mul_f32 v[18:19], v[18:19], v[22:23]
	v_cvt_pk_bf16_f32 v12, v12, v13
	v_cvt_pk_bf16_f32 v13, v14, v15
	v_cvt_pk_bf16_f32 v14, v16, v17
	v_cvt_pk_bf16_f32 v15, v18, v19
	global_store_dwordx4 v[24:25], v[12:15], off offset:-2048 sc1
	s_nop 1
	global_load_dwordx4 v[12:15], v[34:35], off offset:-2048
	v_mul_f32_e32 v37, 0xbfb8aa3b, v5
	s_waitcnt lgkmcnt(0)
	v_mul_f32_e32 v42, 0xbfb8aa3b, v2
	v_mul_f32_e32 v43, 0xbfb8aa3b, v3
	v_exp_f32_e32 v37, v37
	v_mul_f32_e32 v38, 0xbfb8aa3b, v6
	v_mul_f32_e32 v39, 0xbfb8aa3b, v7
	v_exp_f32_e32 v42, v42
	v_exp_f32_e32 v43, v43
	v_exp_f32_e32 v38, v38
	v_exp_f32_e32 v39, v39
	v_mul_f32_e32 v40, 0xbfb8aa3b, v0
	v_mul_f32_e32 v41, 0xbfb8aa3b, v1
	v_exp_f32_e32 v40, v40
	v_exp_f32_e32 v41, v41
	v_pk_add_f32 v[36:37], v[36:37], 1.0 op_sel_hi:[1,0]
	v_pk_add_f32 v[42:43], v[42:43], 1.0 op_sel_hi:[1,0]
	v_pk_add_f32 v[38:39], v[38:39], 1.0 op_sel_hi:[1,0]
	v_pk_add_f32 v[40:41], v[40:41], 1.0 op_sel_hi:[1,0]
	v_rcp_f32_e32 v16, v37
	s_nop 0
	v_mul_f32_e32 v5, v5, v16
	v_rcp_f32_e32 v16, v36
	s_nop 0
	v_mul_f32_e32 v4, v4, v16
	v_rcp_f32_e32 v16, v39
	s_nop 0
	v_mul_f32_e32 v7, v7, v16
	v_rcp_f32_e32 v16, v38
	s_nop 0
	v_mul_f32_e32 v6, v6, v16
	v_rcp_f32_e32 v16, v41
	s_nop 0
	v_mul_f32_e32 v1, v1, v16
	v_rcp_f32_e32 v16, v40
	s_nop 0
	v_mul_f32_e32 v0, v0, v16
	v_rcp_f32_e32 v16, v43
	s_nop 0
	v_mul_f32_e32 v3, v3, v16
	v_rcp_f32_e32 v16, v42
	s_nop 0
	v_mul_f32_e32 v2, v2, v16
	s_waitcnt vmcnt(0)
	v_lshlrev_b32_e32 v16, 16, v12
	v_and_b32_e32 v17, 0xffff0000, v12
	v_lshlrev_b32_e32 v12, 16, v13
	v_and_b32_e32 v13, 0xffff0000, v13
	v_lshlrev_b32_e32 v18, 16, v14
	v_and_b32_e32 v19, 0xffff0000, v14
	v_lshlrev_b32_e32 v14, 16, v15
	v_and_b32_e32 v15, 0xffff0000, v15
	s_addk_i32 s67, 0x200
	v_pk_mul_f32 v[4:5], v[4:5], v[16:17]
	v_pk_mul_f32 v[6:7], v[6:7], v[12:13]
	v_pk_mul_f32 v[12:13], v[0:1], v[18:19]
	v_pk_mul_f32 v[14:15], v[2:3], v[14:15]
	s_cmpk_lg_i32 s67, 0x800
	v_cvt_pk_bf16_f32 v0, v4, v5
	v_cvt_pk_bf16_f32 v1, v6, v7
	v_cvt_pk_bf16_f32 v2, v12, v13
	v_cvt_pk_bf16_f32 v3, v14, v15
	global_store_dwordx4 v[34:35], v[0:3], off offset:-2048 sc1
	s_cbranch_scc1 .LBB0_385
	s_barrier
	s_branch .LBB0_353
.LBB0_387:
	v_readlane_b32 s42, v247, 0
	v_readlane_b32 s43, v247, 1
	s_waitcnt vmcnt(0)
	s_barrier
	s_and_saveexec_b64 s[4:5], s[42:43]
	s_cbranch_execz .LBB0_393
	s_waitcnt vmcnt(0)
	v_mov_b32_e32 v0, 0
	v_mov_b32_e32 v1, 1
	global_atomic_add v1, v0, v1, s[44:45] sc0
	s_mul_i32 s2, s3, 3
	s_waitcnt vmcnt(0)
	v_readfirstlane_b32 s6, v1
	s_nop 3
	s_add_i32 s6, s6, 1
	s_cmp_eq_u32 s6, s2
	s_cbranch_scc0 .Lgbar4_poll
	v_mov_b32_e32 v1, 1
	global_atomic_add v0, v1, s[44:45] offset:1280
	global_atomic_add v0, v1, s[44:45] offset:1344
	global_atomic_add v0, v1, s[44:45] offset:1408
	global_atomic_add v0, v1, s[44:45] offset:1472
	global_atomic_add v0, v1, s[44:45] offset:1536
	global_atomic_add v0, v1, s[44:45] offset:1600
	global_atomic_add v0, v1, s[44:45] offset:1664
	global_atomic_add v0, v1, s[44:45] offset:1728
	s_branch .Lgbar4_done

; __device__ __forceinline__ float bflo(unsigned v) { return __uint_as_float(v << 16); }
; __device__ __forceinline__ float bfhi(unsigned v) { return __uint_as_float(v & 0xffff0000u); }
; __device__ __forceinline__ uint4 pack8(float4 a, float4 b) { uint4 o; o.x = cvtpk(a.x, a.y); o.y = cvtpk(a.z, a.w); o.z = cvtpk(b.x, b.y); o.w = cvtpk(b.z, b.w); return o; }
; __device__ __forceinline__ void phase5(const Params& p, unsigned char* smem) {
;     ...
;     epilogue_rows(acc, m0, n0, smem, [&](int m, int n, float4 a, float4 b) {
;       uint4 g = *(const uint4*)(SGA + (size_t)m * 1024 + n);
;       a.x *= bflo(g.x); a.y *= bfhi(g.x); a.z *= bflo(g.y); a.w *= bfhi(g.y); b.x *= bflo(g.z); b.y *= bfhi(g.z); b.z *= bflo(g.w); b.w *= bfhi(g.w);
;       *(uint4*)(MERGED + (size_t)m * 1024 + n) = pack8(a, b);
;     });
.LBB0_404:
	v_add_u32_e32 v10, s14, v1
	v_ashrrev_i32_e32 v11, 4, v10
	v_add_u32_e32 v6, s26, v11
	v_ashrrev_i32_e32 v7, 31, v6
	v_lshlrev_b64 v[18:19], 11, v[6:7]
	v_lshl_add_u64 v[6:7], v[2:3], 0, v[18:19]
	global_load_dwordx4 v[6:9], v[6:7], off
	v_add_u32_e32 v10, 0x100, v10
	v_mad_u64_u32 v[14:15], s[16:17], v11, s24, v[0:1]
	v_ashrrev_i32_e32 v28, 4, v10
	ds_read_b128 v[10:13], v14
	ds_read_b128 v[14:17], v14 offset:16
	v_add_u32_e32 v20, s26, v28
	v_ashrrev_i32_e32 v21, 31, v20
	v_lshl_add_u64 v[18:19], v[4:5], 0, v[18:19]
	v_lshlrev_b64 v[20:21], 11, v[20:21]
	v_lshl_add_u64 v[22:23], v[2:3], 0, v[20:21]
	s_addk_i32 s14, 0x200
	s_cmpk_lg_i32 s14, 0x800
	s_waitcnt vmcnt(0)
	v_lshlrev_b32_e32 v24, 16, v6
	v_and_b32_e32 v25, 0xffff0000, v6
	v_lshlrev_b32_e32 v6, 16, v7
	v_and_b32_e32 v7, 0xffff0000, v7
	v_lshlrev_b32_e32 v26, 16, v8
	v_and_b32_e32 v27, 0xffff0000, v8
	v_lshlrev_b32_e32 v8, 16, v9
	v_and_b32_e32 v9, 0xffff0000, v9
	s_waitcnt lgkmcnt(1)
	v_pk_mul_f32 v[10:11], v[10:11], v[24:25]
	v_pk_mul_f32 v[12:13], v[12:13], v[6:7]
	s_waitcnt lgkmcnt(0)
	v_pk_mul_f32 v[14:15], v[14:15], v[26:27]
	v_pk_mul_f32 v[16:17], v[16:17], v[8:9]
	v_cvt_pk_bf16_f32 v6, v10, v11
	v_cvt_pk_bf16_f32 v7, v12, v13
	v_cvt_pk_bf16_f32 v8, v14, v15
	v_cvt_pk_bf16_f32 v9, v16, v17
	global_store_dwordx4 v[18:19], v[6:9], off sc1
	global_load_dwordx4 v[6:9], v[22:23], off
	v_mad_u64_u32 v[14:15], s[16:17], v28, s24, v[0:1]
	ds_read_b128 v[10:13], v14
	ds_read_b128 v[14:17], v14 offset:16
	v_lshl_add_u64 v[18:19], v[4:5], 0, v[20:21]
	s_waitcnt vmcnt(0)
	v_lshlrev_b32_e32 v20, 16, v6
	v_and_b32_e32 v21, 0xffff0000, v6
	v_lshlrev_b32_e32 v6, 16, v7
	v_and_b32_e32 v7, 0xffff0000, v7
	v_lshlrev_b32_e32 v22, 16, v8
	v_and_b32_e32 v23, 0xffff0000, v8
	v_lshlrev_b32_e32 v8, 16, v9
	v_and_b32_e32 v9, 0xffff0000, v9
	s_waitcnt lgkmcnt(1)
	v_pk_mul_f32 v[10:11], v[10:11], v[20:21]
	v_pk_mul_f32 v[12:13], v[12:13], v[6:7]
	s_waitcnt lgkmcnt(0)
	v_pk_mul_f32 v[14:15], v[14:15], v[22:23]
	v_pk_mul_f32 v[16:17], v[16:17], v[8:9]
	v_cvt_pk_bf16_f32 v6, v10, v11
	v_cvt_pk_bf16_f32 v7, v12, v13
	v_cvt_pk_bf16_f32 v8, v14, v15
	v_cvt_pk_bf16_f32 v9, v16, v17
	global_store_dwordx4 v[18:19], v[6:9], off sc1
	s_cbranch_scc1 .LBB0_404
	s_add_i32 s25, s25, s65
	s_lshr_b32 s14, s25, 3
	s_and_b32 s16, s14, 0xffffff8
	s_cmpk_gt_u32 s25, 0x7f
	s_cselect_b64 s[14:15], -1, 0
	s_barrier
	s_branch .LBB0_395

; __device__ __forceinline__ float bflo(unsigned v) { return __uint_as_float(v << 16); }
; __device__ __forceinline__ float bfhi(unsigned v) { return __uint_as_float(v & 0xffff0000u); }
; __device__ __forceinline__ uint4 pack8(float4 a, float4 b) { uint4 o; o.x = cvtpk(a.x, a.y); o.y = cvtpk(a.z, a.w); o.z = cvtpk(b.x, b.y); o.w = cvtpk(b.z, b.w); return o; }
; __device__ __forceinline__ void grid_barrier(unsigned* ctr, const unsigned k) {
;   __syncthreads();
;   if (threadIdx.x == 0) {
;     __hip_atomic_fetch_add(ctr, 1u, __ATOMIC_RELEASE, __HIP_MEMORY_SCOPE_AGENT);
;     const unsigned target = k * gridDim.x;
;     while (__hip_atomic_load(ctr, __ATOMIC_RELAXED, __HIP_MEMORY_SCOPE_AGENT) < target) __builtin_amdgcn_s_sleep(1);
;     __builtin_amdgcn_fence(__ATOMIC_ACQUIRE, "agent");
;   }
;   __syncthreads();
; __device__ __forceinline__ void phase5(const Params& p, unsigned char* smem) {
;     ...
;     epilogue_rows(acc, m0, n0, smem, [&](int m, int n, float4 a, float4 b) {
;       uint4 g = *(const uint4*)(SGD + (size_t)m * 1024 + n);
;       uint4* ptr = (uint4*)(MERGED + (size_t)m * 1024 + n);
;       uint4 o = *ptr;
;       a.x = bflo(o.x) + a.x * bflo(g.x); a.y = bfhi(o.x) + a.y * bfhi(g.x); a.z = bflo(o.y) + a.z * bflo(g.y); a.w = bfhi(o.y) + a.w * bfhi(g.y);
;       b.x = bflo(o.z) + b.x * bflo(g.z); b.y = bfhi(o.z) + b.y * bfhi(g.z); b.z = bflo(o.w) + b.z * bflo(g.w); b.w = bfhi(o.w) + b.w * bfhi(g.w);
;       *ptr = pack8(a, b);
;     });
.LBB0_416:
	v_add_u32_e32 v16, s14, v1
	v_ashrrev_i32_e32 v17, 4, v16
	v_add_u32_e32 v6, s29, v17
	v_ashrrev_i32_e32 v7, 31, v6
	v_lshlrev_b64 v[6:7], 11, v[6:7]
	v_lshl_add_u64 v[22:23], v[4:5], 0, v[6:7]
	v_lshl_add_u64 v[14:15], v[2:3], 0, v[6:7]
	global_load_dwordx4 v[6:9], v[22:23], off
	global_load_dwordx4 v[10:13], v[14:15], off
	v_add_u32_e32 v14, 0x100, v16
	v_mad_u64_u32 v[18:19], s[16:17], v17, s27, v[0:1]
	v_ashrrev_i32_e32 v36, 4, v14
	ds_read_b128 v[14:17], v18
	ds_read_b128 v[18:21], v18 offset:16
	v_add_u32_e32 v24, s29, v36
	v_ashrrev_i32_e32 v25, 31, v24
	v_lshlrev_b64 v[24:25], 11, v[24:25]
	v_lshl_add_u64 v[26:27], v[2:3], 0, v[24:25]
	v_lshl_add_u64 v[24:25], v[4:5], 0, v[24:25]
	s_addk_i32 s14, 0x200
	s_cmpk_lg_i32 s14, 0x800
	s_waitcnt vmcnt(1)
	v_lshlrev_b32_e32 v28, 16, v6
	s_waitcnt vmcnt(0)
	v_lshlrev_b32_e32 v30, 16, v10
	v_and_b32_e32 v29, 0xffff0000, v6
	v_and_b32_e32 v31, 0xffff0000, v10
	v_lshlrev_b32_e32 v6, 16, v7
	v_lshlrev_b32_e32 v10, 16, v11
	v_and_b32_e32 v7, 0xffff0000, v7
	v_and_b32_e32 v11, 0xffff0000, v11
	v_lshlrev_b32_e32 v32, 16, v8
	v_lshlrev_b32_e32 v34, 16, v12
	v_and_b32_e32 v33, 0xffff0000, v8
	v_and_b32_e32 v35, 0xffff0000, v12
	v_lshlrev_b32_e32 v8, 16, v9
	v_lshlrev_b32_e32 v12, 16, v13
	v_and_b32_e32 v9, 0xffff0000, v9
	v_and_b32_e32 v13, 0xffff0000, v13
	s_waitcnt lgkmcnt(1)
	v_pk_fma_f32 v[14:15], v[14:15], v[30:31], v[28:29]
	v_pk_fma_f32 v[10:11], v[16:17], v[10:11], v[6:7]
	s_waitcnt lgkmcnt(0)
	v_pk_fma_f32 v[16:17], v[18:19], v[34:35], v[32:33]
	v_pk_fma_f32 v[12:13], v[20:21], v[12:13], v[8:9]
	v_cvt_pk_bf16_f32 v6, v14, v15
	v_cvt_pk_bf16_f32 v7, v10, v11
	v_cvt_pk_bf16_f32 v8, v16, v17
	v_cvt_pk_bf16_f32 v9, v12, v13
	global_store_dwordx4 v[22:23], v[6:9], off sc1
	global_load_dwordx4 v[6:9], v[24:25], off
	s_nop 0
	global_load_dwordx4 v[10:13], v[26:27], off
	v_mad_u64_u32 v[18:19], s[16:17], v36, s27, v[0:1]
	ds_read_b128 v[14:17], v18
	ds_read_b128 v[18:21], v18 offset:16
	s_waitcnt vmcnt(1)
	v_lshlrev_b32_e32 v22, 16, v6
	s_waitcnt vmcnt(0)
	v_lshlrev_b32_e32 v26, 16, v10
	v_and_b32_e32 v23, 0xffff0000, v6
	v_and_b32_e32 v27, 0xffff0000, v10
	v_lshlrev_b32_e32 v6, 16, v7
	v_lshlrev_b32_e32 v10, 16, v11
	v_and_b32_e32 v7, 0xffff0000, v7
	v_and_b32_e32 v11, 0xffff0000, v11
	v_lshlrev_b32_e32 v28, 16, v8
	v_lshlrev_b32_e32 v30, 16, v12
	v_and_b32_e32 v29, 0xffff0000, v8
	v_and_b32_e32 v31, 0xffff0000, v12
	v_lshlrev_b32_e32 v8, 16, v9
	v_lshlrev_b32_e32 v12, 16, v13
	v_and_b32_e32 v9, 0xffff0000, v9
	v_and_b32_e32 v13, 0xffff0000, v13
	s_waitcnt lgkmcnt(1)
	v_pk_fma_f32 v[14:15], v[14:15], v[26:27], v[22:23]
	v_pk_fma_f32 v[10:11], v[16:17], v[10:11], v[6:7]
	s_waitcnt lgkmcnt(0)
	v_pk_fma_f32 v[16:17], v[18:19], v[30:31], v[28:29]
	v_pk_fma_f32 v[12:13], v[20:21], v[12:13], v[8:9]
	v_cvt_pk_bf16_f32 v6, v14, v15
	v_cvt_pk_bf16_f32 v7, v10, v11
	v_cvt_pk_bf16_f32 v8, v16, v17
	v_cvt_pk_bf16_f32 v9, v12, v13
	global_store_dwordx4 v[24:25], v[6:9], off sc1
	s_cbranch_scc1 .LBB0_416
	s_add_i32 s28, s28, s65
	s_lshr_b32 s14, s28, 3
	s_and_b32 s18, s14, 0x7fffff8
	s_cmpk_gt_u32 s28, 0x7f
	s_cselect_b64 s[16:17], -1, 0
	s_barrier
	s_branch .LBB0_407
.LBB0_418:
	s_waitcnt vmcnt(0)
	s_barrier
	s_and_saveexec_b64 s[6:7], s[42:43]
	s_cbranch_execz .LBB0_424
	s_waitcnt vmcnt(0)
	v_mov_b32_e32 v0, 0
	v_mov_b32_e32 v1, 1
	global_atomic_add v1, v0, v1, s[44:45] sc0
	s_lshl_b32 s2, s3, 2
	s_waitcnt vmcnt(0)
	v_readfirstlane_b32 s8, v1
	s_nop 3
	s_add_i32 s8, s8, 1
	s_cmp_eq_u32 s8, s2
	s_cbranch_scc0 .Lgbar5_poll
	v_mov_b32_e32 v1, 1
	global_atomic_add v0, v1, s[44:45] offset:1280
	global_atomic_add v0, v1, s[44:45] offset:1344
	global_atomic_add v0, v1, s[44:45] offset:1408
	global_atomic_add v0, v1, s[44:45] offset:1472
	global_atomic_add v0, v1, s[44:45] offset:1536
	global_atomic_add v0, v1, s[44:45] offset:1600
	global_atomic_add v0, v1, s[44:45] offset:1664
	global_atomic_add v0, v1, s[44:45] offset:1728
	s_branch .Lgbar5_done

; __device__ __forceinline__ int ltid() { int t = threadIdx.x; asm volatile("" : "+v"(t)); return t; }
; __device__ __forceinline__ void grid_barrier(unsigned* ctr, const unsigned k) {
;   __syncthreads();
;   if (threadIdx.x == 0) {
;     __hip_atomic_fetch_add(ctr, 1u, __ATOMIC_RELEASE, __HIP_MEMORY_SCOPE_AGENT);
;     const unsigned target = k * gridDim.x;
;     while (__hip_atomic_load(ctr, __ATOMIC_RELAXED, __HIP_MEMORY_SCOPE_AGENT) < target) __builtin_amdgcn_s_sleep(1);
;     __builtin_amdgcn_fence(__ATOMIC_ACQUIRE, "agent");
;   }
;   __syncthreads();
; __device__ __forceinline__ void phase6(const Params& p, unsigned char* smem) {
;     ...
;     epilogue_rows(acc, m0, n0, smem, [&](int m, int n, float4 a, float4 b) {
;       const float4* xp = (const float4*)(p.x + (size_t)m * 1024 + n);
;       float4 x0 = xp[0], x1 = xp[1];
;       a.x += x0.x; a.y += x0.y; a.z += x0.z; a.w += x0.w; b.x += x1.x; b.y += x1.y; b.z += x1.z; b.w += x1.w;
;       float4* op = (float4*)(p.out + (size_t)m * 1024 + n);
;       op[0] = a; op[1] = b;
;       float sq = a.x * a.x + a.y * a.y + a.z * a.z + a.w * a.w + b.x * b.x + b.y * b.y + b.z * b.z + b.w * b.w;
;       sq += __shfl_xor(sq, 1); sq += __shfl_xor(sq, 2); sq += __shfl_xor(sq, 4); sq += __shfl_xor(sq, 8);
;       if ((ltid() & 15) == 0) PSUM[(size_t)nt * NX + m] = sq;
.LBB0_437:
	v_add_u32_e32 v12, s24, v1
	s_waitcnt lgkmcnt(0)
	v_ashrrev_i32_e32 v13, 4, v12
	v_add_u32_e32 v6, s38, v13
	v_ashrrev_i32_e32 v7, 31, v6
	v_lshlrev_b64 v[30:31], 12, v[6:7]
	v_lshl_add_u64 v[22:23], v[2:3], 0, v[30:31]
	global_load_dwordx4 v[14:17], v[22:23], off
	global_load_dwordx4 v[18:21], v[22:23], off offset:16
	v_mad_u64_u32 v[26:27], s[22:23], v13, s35, v[0:1]
	ds_read_b128 v[22:25], v26
	ds_read_b128 v[26:29], v26 offset:16
	s_waitcnt vmcnt(1) lgkmcnt(1)
	v_pk_add_f32 v[14:15], v[22:23], v[14:15]
	v_pk_add_f32 v[16:17], v[24:25], v[16:17]
	v_pk_mul_f32 v[22:23], v[14:15], v[14:15]
	v_pk_mul_f32 v[24:25], v[16:17], v[16:17]
	v_add_f32_e32 v13, v22, v23
	s_waitcnt vmcnt(0) lgkmcnt(0)
	v_pk_add_f32 v[18:19], v[26:27], v[18:19]
	v_add_f32_e32 v13, v13, v24
	v_pk_mul_f32 v[26:27], v[18:19], v[18:19]
	v_add_f32_e32 v13, v13, v25
	v_pk_add_f32 v[20:21], v[28:29], v[20:21]
	v_add_f32_e32 v13, v13, v26
	v_pk_mul_f32 v[28:29], v[20:21], v[20:21]
	v_add_f32_e32 v13, v13, v27
	v_add_f32_e32 v13, v13, v28
	v_add_f32_e32 v13, v13, v29
	ds_bpermute_b32 v22, v8, v13
	s_waitcnt lgkmcnt(0)
	v_add_f32_e32 v13, v13, v22
	ds_bpermute_b32 v22, v9, v13
	s_waitcnt lgkmcnt(0)
	v_add_f32_e32 v13, v13, v22
	ds_bpermute_b32 v24, v10, v13
	v_lshl_add_u64 v[22:23], v[4:5], 0, v[30:31]
	global_store_dwordx4 v[22:23], v[14:17], off sc1
	global_store_dwordx4 v[22:23], v[18:21], off offset:16 sc1
	s_waitcnt lgkmcnt(0)
	v_add_f32_e32 v13, v13, v24
	ds_bpermute_b32 v14, v11, v13
	v_mov_b32_e32 v15, v218
	s_nop 0
	v_and_b32_e32 v15, 15, v15
	v_cmp_eq_u32_e32 vcc, 0, v15
	s_and_saveexec_b64 s[22:23], vcc
	s_cbranch_execz .LBB0_439
	s_waitcnt lgkmcnt(0)
	v_add_f32_e32 v13, v13, v14
	v_lshl_add_u64 v[6:7], v[6:7], 2, s[20:21]
	global_store_dword v[6:7], v13, off sc1
.LBB0_439:
	s_or_b64 exec, exec, s[22:23]
	v_add_u32_e32 v6, 0x100, v12
	v_ashrrev_i32_e32 v22, 4, v6
	v_add_u32_e32 v6, s38, v22
	v_ashrrev_i32_e32 v7, 31, v6
	v_lshlrev_b64 v[28:29], 12, v[6:7]
	v_lshl_add_u64 v[20:21], v[2:3], 0, v[28:29]
	s_waitcnt lgkmcnt(0)
	global_load_dwordx4 v[12:15], v[20:21], off
	global_load_dwordx4 v[16:19], v[20:21], off offset:16
	v_mad_u64_u32 v[24:25], s[22:23], v22, s35, v[0:1]
	ds_read_b128 v[20:23], v24
	ds_read_b128 v[24:27], v24 offset:16
	s_waitcnt vmcnt(1) lgkmcnt(1)
	v_pk_add_f32 v[12:13], v[20:21], v[12:13]
	v_pk_add_f32 v[14:15], v[22:23], v[14:15]
	v_pk_mul_f32 v[20:21], v[12:13], v[12:13]
	v_pk_mul_f32 v[22:23], v[14:15], v[14:15]
	v_add_f32_e32 v20, v20, v21
	s_waitcnt vmcnt(0) lgkmcnt(0)
	v_pk_add_f32 v[16:17], v[24:25], v[16:17]
	v_add_f32_e32 v20, v20, v22
	v_pk_mul_f32 v[24:25], v[16:17], v[16:17]
	v_add_f32_e32 v20, v20, v23
	v_pk_add_f32 v[18:19], v[26:27], v[18:19]
	v_add_f32_e32 v20, v20, v24
	v_pk_mul_f32 v[26:27], v[18:19], v[18:19]
	v_add_f32_e32 v20, v20, v25
	v_add_f32_e32 v20, v20, v26
	v_add_f32_e32 v20, v20, v27
	ds_bpermute_b32 v21, v8, v20
	s_waitcnt lgkmcnt(0)
	v_add_f32_e32 v20, v20, v21
	ds_bpermute_b32 v21, v9, v20
	s_waitcnt lgkmcnt(0)
	v_add_f32_e32 v22, v20, v21
	ds_bpermute_b32 v23, v10, v22
	v_lshl_add_u64 v[20:21], v[4:5], 0, v[28:29]
	global_store_dwordx4 v[20:21], v[12:15], off sc1
	global_store_dwordx4 v[20:21], v[16:19], off offset:16 sc1
	s_nop 0
	v_mov_b32_e32 v14, v218
	s_waitcnt lgkmcnt(0)
	v_add_f32_e32 v12, v22, v23
	ds_bpermute_b32 v13, v11, v12
	s_nop 0
	v_and_b32_e32 v14, 15, v14
	v_cmp_eq_u32_e32 vcc, 0, v14
	s_and_saveexec_b64 s[22:23], vcc
	s_cbranch_execz .LBB0_436
	s_waitcnt lgkmcnt(0)
	v_add_f32_e32 v12, v12, v13
	v_lshl_add_u64 v[6:7], v[6:7], 2, s[20:21]
	global_store_dword v[6:7], v12, off sc1
	s_branch .LBB0_436
.LBB0_441:
	s_waitcnt lgkmcnt(0)
	s_waitcnt vmcnt(0)
	s_barrier
	s_and_saveexec_b64 s[4:5], s[42:43]
	s_cbranch_execz .LBB0_447
	s_waitcnt vmcnt(0)
	v_mov_b32_e32 v0, 0
	v_mov_b32_e32 v1, 1
	global_atomic_add v1, v0, v1, s[44:45] sc0
	s_mul_i32 s2, s3, 5
	s_waitcnt vmcnt(0)
	v_readfirstlane_b32 s6, v1
	s_nop 3
	s_add_i32 s6, s6, 1
	s_cmp_eq_u32 s6, s2
	s_cbranch_scc0 .Lgbar6_poll
	v_mov_b32_e32 v1, 1
	global_atomic_add v0, v1, s[44:45] offset:1280
	global_atomic_add v0, v1, s[44:45] offset:1344
	global_atomic_add v0, v1, s[44:45] offset:1408
	global_atomic_add v0, v1, s[44:45] offset:1472
	global_atomic_add v0, v1, s[44:45] offset:1536
	global_atomic_add v0, v1, s[44:45] offset:1600
	global_atomic_add v0, v1, s[44:45] offset:1664
	global_atomic_add v0, v1, s[44:45] offset:1728
	s_branch .Lgbar6_done
